# P5 (LayerNorm1): f32 h rows stored with nt (only re-read in P9, after ~1 GB of other traffic) so the write stream does not evict the bf16 copy the next GEMM reads
# speedup vs baseline: 1.0370x; 1.0060x over previous
; __global__ void __launch_bounds__(NTHREADS, 2) fwd_megakernel(Args args) {
;     ...
;     for (int m = gw; m < MTOK; m += NGW) {
;         float* row = HF + (size_t)m * DM; const float* xr = x + (size_t)m * DM; const bf16* mr = MIXB + (size_t)m * DM; f32x4 v[8]; float s = 0.f;
; #pragma unroll
;         for (int j = 0; j < 8; ++j) { const int c = 4 * (lane + 64 * j); const f32x4 xv = __builtin_nontemporal_load((const f32x4*)(xr + c)); const v2u mv = *(const v2u*)(mr + c);
;             v[j] = xv * ALPHA + (f32x4){bflo(mv.x), bfhi(mv.x), bflo(mv.y), bfhi(mv.y)}; s += (v[j][0] + v[j][1]) + (v[j][2] + v[j][3]); }
;         const float mean = wave_sum(s) * (1.f / DM); float s2 = 0.f;
.LBB0_342:
	v_lshl_add_u64 v[32:33], s[12:13], 0, v[30:31]
	v_add_co_u32_e64 v78, s[4:5], s1, v32
	v_lshl_add_u64 v[48:49], s[40:41], 0, v[30:31]
	s_nop 0
	v_addc_co_u32_e64 v79, s[4:5], 0, v33, s[4:5]
	v_lshl_add_u64 v[36:37], s[40:41], 0, v[28:29]
	global_load_dwordx4 v[38:41], v[32:33], off nt
	global_load_dwordx4 v[42:45], v[32:33], off offset:1024 nt
	global_load_dwordx4 v[50:53], v[32:33], off offset:2048 nt
	global_load_dwordx4 v[62:65], v[32:33], off offset:3072 nt
	v_add_co_u32_e64 v32, s[4:5], s22, v48
	v_add_co_u32_e32 v46, vcc, 0xfc00000, v36
	s_nop 0
	v_addc_co_u32_e64 v33, s[4:5], 0, v49, s[4:5]
	v_add_co_u32_e64 v34, s[4:5], s21, v36
	v_addc_co_u32_e32 v47, vcc, 0, v37, vcc
	s_nop 0
	v_addc_co_u32_e64 v35, s[4:5], 0, v37, s[4:5]
	global_load_dwordx4 v[66:69], v[78:79], off nt
	global_load_dwordx4 v[70:73], v[78:79], off offset:1024 nt
	global_load_dwordx4 v[74:77], v[78:79], off offset:2048 nt
	s_nop 0
	global_load_dwordx4 v[78:81], v[78:79], off offset:3072 nt
	s_nop 0
	global_load_dwordx2 v[36:37], v[46:47], off
	global_load_dwordx2 v[82:83], v[46:47], off offset:512
	global_load_dwordx2 v[84:85], v[46:47], off offset:1024
	global_load_dwordx2 v[86:87], v[46:47], off offset:1536
	global_load_dwordx2 v[88:89], v[46:47], off offset:2048
	global_load_dwordx2 v[90:91], v[46:47], off offset:2560
	global_load_dwordx2 v[92:93], v[46:47], off offset:3072
	s_nop 0
	global_load_dwordx2 v[46:47], v[46:47], off offset:3584
	s_add_i32 s0, s0, s28
	v_lshl_add_u64 v[28:29], v[28:29], 0, s[6:7]
	v_lshl_add_u64 v[30:31], v[30:31], 0, s[8:9]
	s_cmpk_gt_i32 s0, 0x7fff
	s_waitcnt vmcnt(7)
	v_lshlrev_b32_e32 v94, 16, v36
	v_and_b32_e32 v95, 0xffff0000, v36
	v_lshlrev_b32_e32 v36, 16, v37
	v_and_b32_e32 v37, 0xffff0000, v37
	s_waitcnt vmcnt(6)
	v_lshlrev_b32_e32 v96, 16, v82
	v_and_b32_e32 v97, 0xffff0000, v82
	v_lshlrev_b32_e32 v82, 16, v83
	v_and_b32_e32 v83, 0xffff0000, v83
	s_waitcnt vmcnt(5)
	v_lshlrev_b32_e32 v98, 16, v84
	v_and_b32_e32 v99, 0xffff0000, v84
	v_lshlrev_b32_e32 v84, 16, v85
	v_and_b32_e32 v85, 0xffff0000, v85
	s_waitcnt vmcnt(3)
	v_lshlrev_b32_e32 v102, 16, v88
	v_and_b32_e32 v103, 0xffff0000, v88
	v_lshlrev_b32_e32 v88, 16, v89
	v_and_b32_e32 v89, 0xffff0000, v89
	s_waitcnt vmcnt(2)
	v_lshlrev_b32_e32 v104, 16, v90
	v_and_b32_e32 v105, 0xffff0000, v90
	v_lshlrev_b32_e32 v90, 16, v91
	v_and_b32_e32 v91, 0xffff0000, v91
	v_pk_fma_f32 v[112:113], v[40:41], s[10:11], v[36:37] op_sel_hi:[1,0,1]
	v_pk_fma_f32 v[94:95], v[38:39], s[10:11], v[94:95] op_sel_hi:[1,0,1]
	v_pk_fma_f32 v[82:83], v[44:45], s[10:11], v[82:83] op_sel_hi:[1,0,1]
	v_pk_fma_f32 v[96:97], v[42:43], s[10:11], v[96:97] op_sel_hi:[1,0,1]
	s_waitcnt vmcnt(1)
	v_lshlrev_b32_e32 v106, 16, v92
	v_and_b32_e32 v107, 0xffff0000, v92
	v_lshlrev_b32_e32 v92, 16, v93
	v_and_b32_e32 v93, 0xffff0000, v93
	s_waitcnt vmcnt(0)
	v_lshlrev_b32_e32 v108, 16, v46
	v_and_b32_e32 v109, 0xffff0000, v46
	v_lshlrev_b32_e32 v110, 16, v47
	v_and_b32_e32 v111, 0xffff0000, v47
	v_pk_fma_f32 v[84:85], v[52:53], s[10:11], v[84:85] op_sel_hi:[1,0,1]
	v_pk_fma_f32 v[98:99], v[50:51], s[10:11], v[98:99] op_sel_hi:[1,0,1]
	v_pk_fma_f32 v[52:53], v[68:69], s[10:11], v[88:89] op_sel_hi:[1,0,1]
	v_pk_fma_f32 v[50:51], v[66:67], s[10:11], v[102:103] op_sel_hi:[1,0,1]
	v_pk_fma_f32 v[46:47], v[72:73], s[10:11], v[90:91] op_sel_hi:[1,0,1]
	v_pk_fma_f32 v[44:45], v[70:71], s[10:11], v[104:105] op_sel_hi:[1,0,1]
	v_mov_b32_e32 v66, v94
	v_mov_b32_e32 v67, v96
	v_mov_b32_e32 v68, v95
	v_mov_b32_e32 v69, v97
	v_mov_b32_e32 v70, v112
	v_mov_b32_e32 v71, v82
	v_mov_b32_e32 v72, v113
	v_mov_b32_e32 v73, v83
	v_pk_fma_f32 v[42:43], v[76:77], s[10:11], v[92:93] op_sel_hi:[1,0,1]
	v_pk_fma_f32 v[40:41], v[74:75], s[10:11], v[106:107] op_sel_hi:[1,0,1]
	v_pk_mov_b32 v[74:75], v[98:99], v[84:85] op_sel:[1,0]
	v_mov_b32_e32 v76, v98
	v_mov_b32_e32 v77, v85
	v_pk_add_f32 v[66:67], v[66:67], v[68:69]
	v_pk_add_f32 v[68:69], v[70:71], v[72:73]
	v_lshlrev_b32_e32 v100, 16, v86
	v_and_b32_e32 v101, 0xffff0000, v86
	v_lshlrev_b32_e32 v86, 16, v87
	v_and_b32_e32 v87, 0xffff0000, v87
	v_pk_add_f32 v[70:71], v[74:75], v[76:77]
	v_pk_add_f32 v[66:67], v[66:67], v[68:69]
	v_pk_fma_f32 v[64:65], v[64:65], s[10:11], v[86:87] op_sel_hi:[1,0,1]
	v_pk_fma_f32 v[62:63], v[62:63], s[10:11], v[100:101] op_sel_hi:[1,0,1]
	v_pk_add_f32 v[68:69], v[70:71], v[70:71] op_sel:[0,1] op_sel_hi:[1,0]
	v_add_f32_e32 v66, 0, v66
	v_pk_fma_f32 v[38:39], v[80:81], s[10:11], v[110:111] op_sel_hi:[1,0,1]
	v_pk_fma_f32 v[36:37], v[78:79], s[10:11], v[108:109] op_sel_hi:[1,0,1]
	v_add_f32_e32 v78, v62, v63
	v_add_f32_e32 v80, v64, v65
	v_mov_b32_e32 v87, v50
	v_mov_b32_e32 v79, v52
	v_mov_b32_e32 v81, v53
	v_mov_b32_e32 v69, v51
	v_add_f32_e32 v86, v66, v67
	v_pk_mov_b32 v[88:89], v[44:45], v[46:47] op_sel:[1,0]
	v_mov_b32_e32 v90, v44
	v_mov_b32_e32 v91, v47
	v_pk_add_f32 v[72:73], v[78:79], v[80:81]
	v_pk_add_f32 v[66:67], v[86:87], v[68:69]
	v_pk_add_f32 v[74:75], v[88:89], v[90:91]
	v_pk_add_f32 v[66:67], v[66:67], v[72:73]
	v_pk_add_f32 v[70:71], v[74:75], v[74:75] op_sel:[0,1] op_sel_hi:[1,0]
	v_pk_add_f32 v[66:67], v[66:67], v[66:67] op_sel:[0,1] op_sel_hi:[1,0]
	v_add_f32_e32 v92, v40, v41
	v_add_f32_e32 v100, v42, v43
	v_mov_b32_e32 v93, v38
	v_mov_b32_e32 v101, v39
	v_mov_b32_e32 v71, v37
	v_mov_b32_e32 v67, v36
	v_pk_add_f32 v[76:77], v[92:93], v[100:101]
	v_pk_add_f32 v[66:67], v[66:67], v[70:71]
	s_nop 0
	v_pk_add_f32 v[66:67], v[66:67], v[76:77]
	s_nop 0
	v_add_f32_e32 v66, v66, v67
	ds_bpermute_b32 v67, v54, v66
	s_waitcnt lgkmcnt(0)
	v_add_f32_e32 v66, v66, v67
	ds_bpermute_b32 v67, v55, v66
	s_waitcnt lgkmcnt(0)
; __global__ void __launch_bounds__(NTHREADS, 2) fwd_megakernel(Args args) {
;     ...
;         const float mean = wave_sum(s) * (1.f / DM); float s2 = 0.f;
; #pragma unroll
;         for (int j = 0; j < 8; ++j) { v[j] = v[j] - mean; s2 += (v[j][0] * v[j][0] + v[j][1] * v[j][1]) + (v[j][2] * v[j][2] + v[j][3] * v[j][3]); }
	v_add_f32_e32 v66, v66, v67
	ds_bpermute_b32 v67, v56, v66
	s_waitcnt lgkmcnt(0)
	v_add_f32_e32 v66, v66, v67
	ds_bpermute_b32 v67, v57, v66
	s_waitcnt lgkmcnt(0)
	v_add_f32_e32 v66, v66, v67
	ds_bpermute_b32 v67, v58, v66
	s_waitcnt lgkmcnt(0)
	v_add_f32_e32 v66, v66, v67
	ds_bpermute_b32 v67, v59, v66
	s_waitcnt lgkmcnt(0)
	v_add_f32_e32 v66, v66, v67
	v_fmamk_f32 v113, v66, 0xba000000, v113
	v_fmamk_f32 v95, v66, 0xba000000, v95
	v_fmamk_f32 v83, v66, 0xba000000, v83
	v_fmamk_f32 v97, v66, 0xba000000, v97
	v_fmac_f32_e32 v112, 0xba000000, v66
	v_fmac_f32_e32 v94, 0xba000000, v66
	v_fmac_f32_e32 v82, 0xba000000, v66
	v_fmac_f32_e32 v96, 0xba000000, v66
	v_fmamk_f32 v99, v66, 0xba000000, v99
	v_fmac_f32_e32 v98, 0xba000000, v66
	v_fmamk_f32 v85, v66, 0xba000000, v85
	v_fmac_f32_e32 v84, 0xba000000, v66
	v_mov_b32_e32 v68, v95
	v_mov_b32_e32 v69, v97
	v_mov_b32_e32 v72, v113
	v_mov_b32_e32 v73, v83
	v_fmamk_f32 v63, v66, 0xba000000, v63
	v_fmac_f32_e32 v62, 0xba000000, v66
	v_fmamk_f32 v65, v66, 0xba000000, v65
	v_fmac_f32_e32 v64, 0xba000000, v66
	v_fmamk_f32 v53, v66, 0xba000000, v53
	v_fmac_f32_e32 v52, 0xba000000, v66
	v_fmamk_f32 v51, v66, 0xba000000, v51
	v_fmac_f32_e32 v50, 0xba000000, v66
	v_fmamk_f32 v45, v66, 0xba000000, v45
	v_fmac_f32_e32 v44, 0xba000000, v66
	v_fmamk_f32 v47, v66, 0xba000000, v47
	v_fmac_f32_e32 v46, 0xba000000, v66
	v_fmamk_f32 v41, v66, 0xba000000, v41
	v_fmac_f32_e32 v40, 0xba000000, v66
	v_fmamk_f32 v43, v66, 0xba000000, v43
	v_fmac_f32_e32 v42, 0xba000000, v66
	v_fmamk_f32 v39, v66, 0xba000000, v39
	v_fmac_f32_e32 v38, 0xba000000, v66
	v_fmamk_f32 v37, v66, 0xba000000, v37
	v_fmac_f32_e32 v36, 0xba000000, v66
	v_mov_b32_e32 v66, v94
	v_mov_b32_e32 v67, v96
	v_mov_b32_e32 v70, v112
	v_mov_b32_e32 v71, v82
	v_pk_mul_f32 v[74:75], v[84:85], v[84:85]
	v_pk_mul_f32 v[76:77], v[98:99], v[98:99]
	v_pk_mul_f32 v[68:69], v[68:69], v[68:69]
	v_pk_mul_f32 v[72:73], v[72:73], v[72:73]
	v_pk_mov_b32 v[100:101], v[76:77], v[74:75] op_sel:[1,0]
	v_mov_b32_e32 v77, v75
	v_pk_fma_f32 v[66:67], v[66:67], v[66:67], v[68:69]
	v_pk_fma_f32 v[68:69], v[70:71], v[70:71], v[72:73]
	v_mul_f32_e32 v78, v63, v63
	v_mul_f32_e32 v80, v65, v65
	v_pk_add_f32 v[70:71], v[100:101], v[76:77]
	v_pk_add_f32 v[66:67], v[66:67], v[68:69]
	v_mul_f32_e32 v93, v50, v50
	v_mul_f32_e32 v102, v51, v51
	v_mul_f32_e32 v103, v52, v52
	v_mul_f32_e32 v104, v53, v53
	v_pk_fma_f32 v[74:75], v[62:63], v[62:63], v[78:79] op_sel_hi:[1,1,0]
	v_pk_fma_f32 v[78:79], v[64:65], v[64:65], v[80:81] op_sel_hi:[1,1,0]
	v_pk_add_f32 v[68:69], v[70:71], v[70:71] op_sel:[0,1] op_sel_hi:[1,0]
	v_pk_add_f32 v[66:67], v[66:67], v[66:67] op_sel:[0,1] op_sel_hi:[1,0]
	v_pk_mul_f32 v[86:87], v[46:47], v[46:47]
	v_pk_mul_f32 v[88:89], v[44:45], v[44:45]
	v_mov_b32_e32 v75, v103
	v_mov_b32_e32 v79, v104
	v_mov_b32_e32 v69, v102
	v_mov_b32_e32 v67, v93
	v_pk_mov_b32 v[80:81], v[88:89], v[86:87] op_sel:[1,0]
	v_mov_b32_e32 v89, v87
	v_pk_add_f32 v[70:71], v[74:75], v[78:79]
	v_pk_add_f32 v[66:67], v[66:67], v[68:69]
	v_mul_f32_e32 v90, v41, v41
	v_mul_f32_e32 v92, v43, v43
	v_pk_add_f32 v[72:73], v[80:81], v[88:89]
	v_pk_add_f32 v[66:67], v[66:67], v[70:71]
	v_mul_f32_e32 v105, v36, v36
	v_mul_f32_e32 v106, v37, v37
	v_mul_f32_e32 v107, v38, v38
	v_mul_f32_e32 v108, v39, v39
	v_pk_fma_f32 v[86:87], v[40:41], v[40:41], v[90:91] op_sel_hi:[1,1,0]
	v_pk_fma_f32 v[90:91], v[42:43], v[42:43], v[92:93] op_sel_hi:[1,1,0]
	v_pk_add_f32 v[72:73], v[72:73], v[72:73] op_sel:[0,1] op_sel_hi:[1,0]
	v_pk_add_f32 v[66:67], v[66:67], v[66:67] op_sel:[0,1] op_sel_hi:[1,0]
	v_mov_b32_e32 v87, v107
	v_mov_b32_e32 v91, v108
	v_mov_b32_e32 v73, v106
	v_mov_b32_e32 v67, v105
	v_pk_add_f32 v[74:75], v[86:87], v[90:91]
	v_pk_add_f32 v[66:67], v[66:67], v[72:73]
	s_nop 0
	v_pk_add_f32 v[66:67], v[66:67], v[74:75]
	s_nop 0
	v_add_f32_e32 v66, v66, v67
	ds_bpermute_b32 v67, v54, v66
	s_waitcnt lgkmcnt(0)
	v_add_f32_e32 v66, v66, v67
	ds_bpermute_b32 v67, v55, v66
	s_waitcnt lgkmcnt(0)
	v_add_f32_e32 v66, v66, v67
	ds_bpermute_b32 v67, v56, v66
	s_waitcnt lgkmcnt(0)
	v_add_f32_e32 v66, v66, v67
	ds_bpermute_b32 v67, v57, v66
	s_waitcnt lgkmcnt(0)
	v_add_f32_e32 v66, v66, v67
	ds_bpermute_b32 v67, v58, v66
	s_waitcnt lgkmcnt(0)
	v_add_f32_e32 v66, v66, v67
	ds_bpermute_b32 v67, v59, v66
	s_waitcnt lgkmcnt(0)
; __device__ __forceinline__ unsigned cvtpk(float lo, float hi) { f32x2_t v = {lo, hi}; bf16x2_t b = __builtin_convertvector(v, bf16x2_t); return __builtin_bit_cast(unsigned, b); }
; __global__ void __launch_bounds__(NTHREADS, 2) fwd_megakernel(Args args) {
;     ...
;         const float rstd = 1.f / sqrtf(wave_sum(s2) * (1.f / DM) + LN_EPS);
; #pragma unroll
;         for (int j = 0; j < 8; ++j) { const int c = 4 * (lane + 64 * j); const f32x4 gg = *(const f32x4*)(ln1_g + c), bb = *(const f32x4*)(ln1_b + c);
;             const f32x4 o = v[j] * rstd * gg + bb; *(f32x4*)(row + c) = o;
;             v2u wv; wv.x = cvtpk(o[0], o[1]); wv.y = cvtpk(o[2], o[3]); *(v2u*)(HB + (size_t)m * DM + c) = wv; }
	v_add_f32_e32 v66, v66, v67
	v_fmamk_f32 v66, v66, 0x3a000000, v60
	v_mul_f32_e32 v67, 0x4f800000, v66
	v_cmp_gt_f32_e32 vcc, s11, v66
	s_nop 1
	v_cndmask_b32_e32 v66, v66, v67, vcc
	v_sqrt_f32_e32 v67, v66
	s_nop 0
	v_add_u32_e32 v68, -1, v67
	v_add_u32_e32 v69, 1, v67
	v_fma_f32 v70, -v68, v67, v66
	v_fma_f32 v71, -v69, v67, v66
	v_cmp_ge_f32_e64 s[4:5], 0, v70
	s_nop 1
	v_cndmask_b32_e64 v67, v67, v68, s[4:5]
	v_cmp_lt_f32_e64 s[4:5], 0, v71
	s_nop 1
	v_cndmask_b32_e64 v67, v67, v69, s[4:5]
	v_mul_f32_e32 v68, 0x37800000, v67
	v_cndmask_b32_e32 v67, v67, v68, vcc
	v_cmp_class_f32_e32 vcc, v66, v61
	s_nop 1
	v_cndmask_b32_e32 v66, v67, v66, vcc
	v_div_scale_f32 v67, s[4:5], v66, v66, 1.0
	v_rcp_f32_e32 v69, v67
	v_div_scale_f32 v68, vcc, 1.0, v66, 1.0
	v_fma_f32 v70, -v67, v69, 1.0
	v_fmac_f32_e32 v69, v70, v69
	v_mul_f32_e32 v70, v68, v69
	v_fma_f32 v71, -v67, v70, v68
	v_fmac_f32_e32 v70, v71, v69
	v_fma_f32 v67, -v67, v70, v68
	v_div_fmas_f32 v67, v67, v69, v70
	v_div_fixup_f32 v66, v67, v66, 1.0
	v_pk_mul_f32 v[68:69], v[66:67], v[94:95] op_sel_hi:[0,1]
	v_pk_mul_f32 v[70:71], v[66:67], v[112:113] op_sel_hi:[0,1]
	v_pk_fma_f32 v[2:3], v[70:71], v[116:117], v[120:121]
	v_pk_fma_f32 v[0:1], v[68:69], v[114:115], v[118:119]
	global_store_dwordx4 v[32:33], v[0:3], off offset:-4096 nt
	v_add_co_u32_e32 v48, vcc, s20, v48
	s_nop 0
	v_cvt_pk_bf16_f32 v0, v0, v1
	v_cvt_pk_bf16_f32 v1, v2, v3
	global_store_dwordx2 v[34:35], v[0:1], off
	v_pk_mul_f32 v[68:69], v[66:67], v[82:83] op_sel_hi:[0,1]
	v_pk_mul_f32 v[70:71], v[66:67], v[96:97] op_sel_hi:[0,1]
	v_addc_co_u32_e32 v49, vcc, 0, v49, vcc
	v_pk_mul_f32 v[64:65], v[66:67], v[64:65] op_sel_hi:[0,1]
	v_pk_mul_f32 v[62:63], v[66:67], v[62:63] op_sel_hi:[0,1]
	v_pk_mul_f32 v[50:51], v[66:67], v[50:51] op_sel_hi:[0,1]
	v_pk_mul_f32 v[46:47], v[66:67], v[46:47] op_sel_hi:[0,1]
	v_pk_mul_f32 v[44:45], v[66:67], v[44:45] op_sel_hi:[0,1]
	v_pk_mul_f32 v[42:43], v[66:67], v[42:43] op_sel_hi:[0,1]
	v_pk_mul_f32 v[40:41], v[66:67], v[40:41] op_sel_hi:[0,1]
	v_pk_mul_f32 v[38:39], v[66:67], v[38:39] op_sel_hi:[0,1]
	v_pk_mul_f32 v[36:37], v[66:67], v[36:37] op_sel_hi:[0,1]
	v_pk_fma_f32 v[0:1], v[70:71], v[122:123], v[126:127]
	v_pk_fma_f32 v[2:3], v[68:69], v[124:125], v[128:129]
	global_store_dwordx4 v[48:49], v[0:3], off offset:1024 nt
	v_pk_mul_f32 v[68:69], v[66:67], v[84:85] op_sel_hi:[0,1]
	v_pk_mul_f32 v[70:71], v[66:67], v[98:99] op_sel_hi:[0,1]
	v_cvt_pk_bf16_f32 v0, v0, v1
	v_cvt_pk_bf16_f32 v1, v2, v3
	global_store_dwordx2 v[34:35], v[0:1], off offset:512
	v_pk_fma_f32 v[0:1], v[70:71], v[130:131], v[134:135]
	v_pk_fma_f32 v[2:3], v[68:69], v[132:133], v[136:137]
	global_store_dwordx4 v[48:49], v[0:3], off offset:2048 nt
	s_nop 1
	v_cvt_pk_bf16_f32 v0, v0, v1
	v_cvt_pk_bf16_f32 v1, v2, v3
	global_store_dwordx2 v[34:35], v[0:1], off offset:1024
	v_pk_fma_f32 v[0:1], v[62:63], v[138:139], v[142:143]
	v_pk_fma_f32 v[2:3], v[64:65], v[140:141], v[144:145]
	global_store_dwordx4 v[48:49], v[0:3], off offset:3072 nt
	v_pk_mul_f32 v[48:49], v[66:67], v[52:53] op_sel_hi:[0,1]
	s_nop 0
	v_cvt_pk_bf16_f32 v0, v0, v1
	v_cvt_pk_bf16_f32 v1, v2, v3
	global_store_dwordx2 v[34:35], v[0:1], off offset:1536
	v_pk_fma_f32 v[0:1], v[50:51], v[146:147], v[150:151]
	v_pk_fma_f32 v[2:3], v[48:49], v[148:149], v[152:153]
	global_store_dwordx4 v[32:33], v[0:3], off nt
	s_nop 1
	v_cvt_pk_bf16_f32 v0, v0, v1
	v_cvt_pk_bf16_f32 v1, v2, v3
	global_store_dwordx2 v[34:35], v[0:1], off offset:2048
	v_pk_fma_f32 v[0:1], v[44:45], v[154:155], v[158:159]
	v_pk_fma_f32 v[2:3], v[46:47], v[156:157], v[160:161]
	global_store_dwordx4 v[32:33], v[0:3], off offset:1024 nt
	s_nop 1
	v_cvt_pk_bf16_f32 v0, v0, v1
	v_cvt_pk_bf16_f32 v1, v2, v3
	global_store_dwordx2 v[34:35], v[0:1], off offset:2560
	v_pk_fma_f32 v[0:1], v[40:41], v[162:163], v[166:167]
	v_pk_fma_f32 v[2:3], v[42:43], v[164:165], v[168:169]
	global_store_dwordx4 v[32:33], v[0:3], off offset:2048 nt
	s_nop 1
	v_cvt_pk_bf16_f32 v0, v0, v1
	v_cvt_pk_bf16_f32 v1, v2, v3
	global_store_dwordx2 v[34:35], v[0:1], off offset:3072
	v_pk_fma_f32 v[0:1], v[36:37], v[170:171], v[174:175]
	v_pk_fma_f32 v[2:3], v[38:39], v[172:173], v[176:177]
	global_store_dwordx4 v[32:33], v[0:3], off offset:3072 nt
	s_nop 1
	v_cvt_pk_bf16_f32 v0, v0, v1
	v_cvt_pk_bf16_f32 v1, v2, v3
	global_store_dwordx2 v[34:35], v[0:1], off offset:3584
	s_cbranch_scc0 .LBB0_342
